# v7 plus odd WGs enter the p@w_ple/output GEMM phase 16us late
# speedup vs baseline: 1.0252x; 1.0063x over previous
;     __device__ void init(int M, int N, int G_, int c_, unsigned long long mask_ = 0ull) { nM = M / BM; nN = mask_ ? __builtin_popcountll(mask_) : N / BM; nwg = nM * nN; G = G_; c = c_; mask = mask_; }
; #define LAUNDER() do { tid = threadIdx.x; asm volatile("" : "+v"(tid)); lane = tid & 63; wid = __builtin_amdgcn_readfirstlane(tid >> 6); bx = blockIdx.x; asm volatile("" : "+s"(bx)); \
;         vcu = (G % 8 == 0) ? (bx % 8) * (G / 8) + bx / 8 : bx; gw = vcu * 8 + wid; ws = P.ws; asm volatile("" : "+s"(ws)); Q.ws = ws; XB = (bf16_t*)(ws + WS_XB); } while (0)
; __global__ void __launch_bounds__(512, 2) trunk_fwd(Params P) {
;     ...
;         LAUNDER();
;         if (PH(12)) {   pg8::Gemm g{(const bf16_t*)(ws + WS_PB), (const bf16_t*)(ws + WS_WPLE), T, DM, PLE}; pg8::StaticOrder S; S.init(T, DM, G, bx);
;             Epi<EPI_MRG_A> E{}; E.O = (bf16_t*)(ws + WS_GP); E.ldc = DM;
;             pg8::gemm_phase(lds, g, S, E); }
.LBB0_672:
	s_or_b64 exec, exec, s[2:3]
	v_mov_b32_e32 v194, v160
	v_writelane_b32 v255, s13, 3
	s_waitcnt lgkmcnt(0)
	s_barrier
	v_readlane_b32 s30, v252, 50
	v_readfirstlane_b32 s0, v194
	s_nop 3
	s_bitcmp1_b32 s30, 0
	s_cbranch_scc0 .Lstagger_p7_done
	s_sleep 127
	s_sleep 127
	s_sleep 127
	s_sleep 127
.Lstagger_p7_done:
	s_nop 1
	v_writelane_b32 v255, s0, 4
	v_readlane_b32 s0, v254, 63
	v_readlane_b32 s1, v255, 0
	s_and_b64 vcc, exec, s[0:1]
	s_mov_b32 s0, s30
	s_cbranch_vccnz .LBB0_674
	s_ashr_i32 s0, s30, 31
	s_lshr_b32 s0, s0, 29
	s_add_i32 s0, s30, s0
	s_and_b32 s1, s0, -8
	s_sub_i32 s1, s30, s1
	v_readlane_b32 s2, v253, 63
	s_mul_i32 s1, s1, s2
	s_ashr_i32 s0, s0, 3
	s_add_i32 s0, s1, s0
